# adds ds_read hoisting in skinny_branch reduction on top of M2/M3 hoisting
# baseline (speedup 1.0000x reference)
.LBB0_2284:
	s_and_b32 s9, s3, 64
	s_and_b32 s8, s2, -16
	s_bitset1_b32 s9, 13
	v_or_b32_e32 v2, s8, v28
	v_or_b32_e32 v4, s9, v28
	v_ashrrev_i32_e32 v3, 31, v2
	v_lshlrev_b32_e32 v196, 13, v4
	v_lshlrev_b64 v[2:3], 13, v[2:3]
	v_lshl_add_u64 v[18:19], v[12:13], 0, v[196:197]
	v_lshl_add_u64 v[16:17], v[10:11], 0, v[2:3]
	v_lshl_add_u64 v[26:27], v[18:19], 0, s[40:41]
	s_mov_b32 s0, 0x20000
	v_lshl_add_u64 v[20:21], v[16:17], 0, s[40:41]
	v_add_co_u32_e32 v98, vcc, s0, v26
	global_load_dwordx4 v[2:5], v[20:21], off
	global_load_dwordx4 v[6:9], v[26:27], off
	v_addc_co_u32_e32 v99, vcc, 0, v27, vcc
	s_mov_b32 s1, 0x40000
	v_add_co_u32_e32 v100, vcc, s1, v26
	s_mov_b32 s11, 0x60000
	s_nop 0
	v_addc_co_u32_e32 v101, vcc, 0, v27, vcc
	v_add_co_u32_e32 v102, vcc, s11, v26
	global_load_dwordx4 v[22:25], v[98:99], off
	global_load_dwordx4 v[46:49], v[100:101], off
	v_addc_co_u32_e32 v103, vcc, 0, v27, vcc
	global_load_dwordx4 v[50:53], v[102:103], off
	global_load_dwordx4 v[54:57], v[20:21], off offset:2048
	v_lshl_add_u64 v[104:105], s[38:39], 1, v[18:19]
	v_add_co_u32_e32 v106, vcc, s0, v104
	global_load_dwordx4 v[74:77], v[20:21], off offset:64
	global_load_dwordx4 v[78:81], v[26:27], off offset:64
	v_addc_co_u32_e32 v107, vcc, 0, v105, vcc
	v_add_co_u32_e32 v108, vcc, s1, v104
	global_load_dwordx4 v[58:61], v[104:105], off
	s_nop 0
	v_addc_co_u32_e32 v109, vcc, 0, v105, vcc
	v_add_co_u32_e32 v110, vcc, s11, v104
	global_load_dwordx4 v[62:65], v[106:107], off
	global_load_dwordx4 v[66:69], v[108:109], off
	v_addc_co_u32_e32 v111, vcc, 0, v105, vcc
	global_load_dwordx4 v[70:73], v[110:111], off
	v_add_u32_e32 v15, v29, v32
	s_waitcnt vmcnt(0)
	v_mfma_f32_16x16x32_bf16 v[6:9], v[2:5], v[6:9], 0
	v_mfma_f32_16x16x32_bf16 v[22:25], v[2:5], v[22:25], 0
	v_mfma_f32_16x16x32_bf16 v[46:49], v[2:5], v[46:49], 0
	v_mfma_f32_16x16x32_bf16 v[2:5], v[2:5], v[50:53], 0
	global_load_dwordx4 v[50:53], v[98:99], off offset:64
	global_load_dwordx4 v[82:85], v[100:101], off offset:64
	global_load_dwordx4 v[86:89], v[20:21], off offset:2112
	global_load_dwordx4 v[90:93], v[102:103], off offset:64
	v_mfma_f32_16x16x32_bf16 v[58:61], v[54:57], v[58:61], 0
	global_load_dwordx4 v[94:97], v[104:105], off offset:64
	v_mfma_f32_16x16x32_bf16 v[62:65], v[54:57], v[62:65], 0
	v_mfma_f32_16x16x32_bf16 v[66:69], v[54:57], v[66:69], 0
	v_mfma_f32_16x16x32_bf16 v[54:57], v[54:57], v[70:73], 0
	global_load_dwordx4 v[70:73], v[106:107], off offset:64
	v_mfma_f32_16x16x32_bf16 v[6:9], v[74:77], v[78:81], v[6:9]
	global_load_dwordx4 v[78:81], v[108:109], off offset:64
	s_waitcnt vmcnt(5)
	v_mfma_f32_16x16x32_bf16 v[46:49], v[74:77], v[82:85], v[46:49]
	global_load_dwordx4 v[82:85], v[20:21], off offset:128
	v_mfma_f32_16x16x32_bf16 v[22:25], v[74:77], v[50:53], v[22:25]
	global_load_dwordx4 v[50:53], v[110:111], off offset:64
	s_waitcnt vmcnt(5)
	v_mfma_f32_16x16x32_bf16 v[2:5], v[74:77], v[90:93], v[2:5]
	global_load_dwordx4 v[74:77], v[26:27], off offset:128
	global_load_dwordx4 v[90:93], v[98:99], off offset:128
	s_waitcnt vmcnt(6)
	v_mfma_f32_16x16x32_bf16 v[58:61], v[86:89], v[94:97], v[58:61]
	s_waitcnt vmcnt(5)
	v_mfma_f32_16x16x32_bf16 v[62:65], v[86:89], v[70:73], v[62:65]
	global_load_dwordx4 v[70:73], v[100:101], off offset:128
	global_load_dwordx4 v[94:97], v[20:21], off offset:2176
	s_waitcnt vmcnt(6)
	v_mfma_f32_16x16x32_bf16 v[66:69], v[86:89], v[78:81], v[66:69]
	global_load_dwordx4 v[78:81], v[102:103], off offset:128
	s_waitcnt vmcnt(5)
	v_mfma_f32_16x16x32_bf16 v[50:53], v[86:89], v[50:53], v[54:57]
	s_nop 2
	global_load_dwordx4 v[54:57], v[104:105], off offset:128
	global_load_dwordx4 v[86:89], v[26:27], off offset:192
	s_waitcnt vmcnt(6)
	v_mfma_f32_16x16x32_bf16 v[6:9], v[82:85], v[74:77], v[6:9]
	global_load_dwordx4 v[74:77], v[20:21], off offset:192
	s_waitcnt vmcnt(5)
	v_mfma_f32_16x16x32_bf16 v[46:49], v[82:85], v[70:73], v[46:49]
	global_load_dwordx4 v[70:73], v[98:99], off offset:192
	v_mfma_f32_16x16x32_bf16 v[22:25], v[82:85], v[90:93], v[22:25]
	s_waitcnt vmcnt(3)
	v_mfma_f32_16x16x32_bf16 v[54:57], v[94:97], v[54:57], v[58:61]
	s_nop 2
	global_load_dwordx4 v[58:61], v[102:103], off offset:192
	v_lshl_add_u64 v[102:103], v[16:17], 0, s[44:45]
	v_mfma_f32_16x16x32_bf16 v[78:81], v[82:85], v[78:81], v[2:5]
	global_load_dwordx4 v[82:85], v[100:101], off offset:192
	s_waitcnt vmcnt(3)
	v_mfma_f32_16x16x32_bf16 v[2:5], v[74:77], v[86:89], v[6:9]
	global_load_dwordx4 v[86:89], v[106:107], off offset:128
	s_waitcnt vmcnt(3)
	v_mfma_f32_16x16x32_bf16 v[6:9], v[74:77], v[70:73], v[22:25]
	s_nop 2
	global_load_dwordx4 v[22:25], v[108:109], off offset:128
	global_load_dwordx4 v[70:73], v[20:21], off offset:2240
	s_waitcnt vmcnt(3)
	v_mfma_f32_16x16x32_bf16 v[46:49], v[74:77], v[82:85], v[46:49]
	global_load_dwordx4 v[82:85], v[110:111], off offset:128
	v_mfma_f32_16x16x32_bf16 v[58:61], v[74:77], v[58:61], v[78:81]
	global_load_dwordx4 v[74:77], v[104:105], off offset:192
	s_nop 1
	global_load_dwordx4 v[78:81], v[106:107], off offset:192
	s_waitcnt vmcnt(4)
	v_mfma_f32_16x16x32_bf16 v[20:23], v[94:97], v[22:25], v[66:69]
	global_load_dwordx4 v[24:27], v[108:109], off offset:192
	v_lshl_add_u64 v[104:105], v[18:19], 0, s[44:45]
	v_add_co_u32_e32 v106, vcc, s0, v104
	global_load_dwordx4 v[66:69], v[110:111], off offset:192
	v_mfma_f32_16x16x32_bf16 v[62:65], v[94:97], v[86:89], v[62:65]
	v_addc_co_u32_e32 v107, vcc, 0, v105, vcc
	v_add_co_u32_e32 v108, vcc, s1, v104
	global_load_dwordx4 v[86:89], v[106:107], off
	s_nop 0
	v_addc_co_u32_e32 v109, vcc, 0, v105, vcc
	v_add_co_u32_e32 v110, vcc, s11, v104
	s_waitcnt vmcnt(5)
	v_mfma_f32_16x16x32_bf16 v[50:53], v[94:97], v[82:85], v[50:53]
	global_load_dwordx4 v[82:85], v[102:103], off
	v_addc_co_u32_e32 v111, vcc, 0, v105, vcc
	s_waitcnt vmcnt(5)
	v_mfma_f32_16x16x32_bf16 v[54:57], v[70:73], v[74:77], v[54:57]
	global_load_dwordx4 v[74:77], v[104:105], off
	s_waitcnt vmcnt(5)
	v_mfma_f32_16x16x32_bf16 v[62:65], v[70:73], v[78:81], v[62:65]
	global_load_dwordx4 v[78:81], v[108:109], off
	s_waitcnt vmcnt(5)
	v_mfma_f32_16x16x32_bf16 v[20:23], v[70:73], v[24:27], v[20:23]
	global_load_dwordx4 v[24:27], v[110:111], off
	global_load_dwordx4 v[90:93], v[102:103], off offset:64
	global_load_dwordx4 v[94:97], v[108:109], off offset:64
	global_load_dwordx4 v[98:101], v[110:111], off offset:64
	s_waitcnt vmcnt(8)
	v_mfma_f32_16x16x32_bf16 v[50:53], v[70:73], v[66:69], v[50:53]
	global_load_dwordx4 v[66:69], v[104:105], off offset:64
	s_waitcnt vmcnt(6)
	v_mfma_f32_16x16x32_bf16 v[70:73], v[82:85], v[74:77], 0
	global_load_dwordx4 v[74:77], v[106:107], off offset:64
	v_mfma_f32_16x16x32_bf16 v[86:89], v[82:85], v[86:89], 0
	s_waitcnt vmcnt(6)
	v_mfma_f32_16x16x32_bf16 v[78:81], v[82:85], v[78:81], 0
	s_waitcnt vmcnt(5)
	v_mfma_f32_16x16x32_bf16 v[24:27], v[82:85], v[24:27], 0
	global_load_dwordx4 v[82:85], v[102:103], off offset:128
	s_waitcnt vmcnt(2)
	v_mfma_f32_16x16x32_bf16 v[66:69], v[90:93], v[66:69], v[70:73]
	s_nop 2
	global_load_dwordx4 v[70:73], v[104:105], off offset:128
	v_mfma_f32_16x16x32_bf16 v[78:81], v[90:93], v[94:97], v[78:81]
	global_load_dwordx4 v[94:97], v[108:109], off offset:128
	v_mfma_f32_16x16x32_bf16 v[24:27], v[90:93], v[98:101], v[24:27]
	s_waitcnt vmcnt(3)
	v_mfma_f32_16x16x32_bf16 v[74:77], v[90:93], v[74:77], v[86:89]
	s_nop 2
	global_load_dwordx4 v[86:89], v[106:107], off offset:128
	global_load_dwordx4 v[90:93], v[110:111], off offset:128
	s_waitcnt vmcnt(3)
	v_mfma_f32_16x16x32_bf16 v[66:69], v[82:85], v[70:73], v[66:69]
	global_load_dwordx4 v[70:73], v[102:103], off offset:192
	s_waitcnt vmcnt(3)
	v_mfma_f32_16x16x32_bf16 v[78:81], v[82:85], v[94:97], v[78:81]
	global_load_dwordx4 v[94:97], v[106:107], off offset:192
	v_lshl_add_u64 v[106:107], v[16:17], 0, s[46:47]
	s_waitcnt vmcnt(3)
	v_mfma_f32_16x16x32_bf16 v[74:77], v[82:85], v[86:89], v[74:77]
	global_load_dwordx4 v[86:89], v[104:105], off offset:192
	s_waitcnt vmcnt(3)
	v_mfma_f32_16x16x32_bf16 v[24:27], v[82:85], v[90:93], v[24:27]
	global_load_dwordx4 v[82:85], v[108:109], off offset:192
	global_load_dwordx4 v[90:93], v[110:111], off offset:192
	v_lshl_add_u64 v[108:109], v[18:19], 0, s[46:47]
	v_add_co_u32_e32 v110, vcc, s0, v108
	s_waitcnt vmcnt(3)
	v_mfma_f32_16x16x32_bf16 v[74:77], v[70:73], v[94:97], v[74:77]
	v_addc_co_u32_e32 v111, vcc, 0, v109, vcc
	v_add_co_u32_e32 v112, vcc, s1, v108
	s_waitcnt vmcnt(1)
	v_mfma_f32_16x16x32_bf16 v[78:81], v[70:73], v[82:85], v[78:81]
	global_load_dwordx4 v[16:19], v[108:109], off
	v_addc_co_u32_e32 v113, vcc, 0, v109, vcc
	v_mfma_f32_16x16x32_bf16 v[66:69], v[70:73], v[86:89], v[66:69]
	global_load_dwordx4 v[86:89], v[106:107], off
	global_load_dwordx4 v[82:85], v[110:111], off
	global_load_dwordx4 v[94:97], v[112:113], off
	v_add_co_u32_e32 v114, vcc, s11, v108
	s_waitcnt vmcnt(4)
	v_mfma_f32_16x16x32_bf16 v[24:27], v[70:73], v[90:93], v[24:27]
	v_addc_co_u32_e32 v115, vcc, 0, v109, vcc
	global_load_dwordx4 v[98:101], v[114:115], off
	global_load_dwordx4 v[102:105], v[106:107], off offset:64
	global_load_dwordx4 v[70:73], v[108:109], off offset:64
	s_waitcnt vmcnt(5)
	v_mfma_f32_16x16x32_bf16 v[16:19], v[86:89], v[16:19], v[66:69]
	s_nop 2
	global_load_dwordx4 v[66:69], v[110:111], off offset:64
	s_waitcnt vmcnt(5)
	v_mfma_f32_16x16x32_bf16 v[74:77], v[86:89], v[82:85], v[74:77]
	global_load_dwordx4 v[82:85], v[112:113], off offset:64
	global_load_dwordx4 v[90:93], v[114:115], off offset:64
	s_waitcnt vmcnt(6)
	v_mfma_f32_16x16x32_bf16 v[78:81], v[86:89], v[94:97], v[78:81]
	global_load_dwordx4 v[94:97], v[106:107], off offset:128
	s_waitcnt vmcnt(6)
	v_mfma_f32_16x16x32_bf16 v[24:27], v[86:89], v[98:101], v[24:27]
	global_load_dwordx4 v[86:89], v[108:109], off offset:128
	s_waitcnt vmcnt(5)
	v_mfma_f32_16x16x32_bf16 v[16:19], v[102:105], v[70:73], v[16:19]
	global_load_dwordx4 v[70:73], v[110:111], off offset:128
	s_waitcnt vmcnt(4)
	v_mfma_f32_16x16x32_bf16 v[78:81], v[102:105], v[82:85], v[78:81]
	v_mfma_f32_16x16x32_bf16 v[66:69], v[102:105], v[66:69], v[74:77]
	s_nop 2
	global_load_dwordx4 v[74:77], v[112:113], off offset:128
	global_load_dwordx4 v[98:101], v[114:115], off offset:128
	global_load_dwordx4 v[82:85], v[106:107], off offset:192
	s_waitcnt vmcnt(6)
	v_mfma_f32_16x16x32_bf16 v[24:27], v[102:105], v[90:93], v[24:27]
	global_load_dwordx4 v[90:93], v[108:109], off offset:192
	s_waitcnt vmcnt(5)
	v_mfma_f32_16x16x32_bf16 v[16:19], v[94:97], v[86:89], v[16:19]
	global_load_dwordx4 v[86:89], v[110:111], off offset:192
	s_waitcnt vmcnt(5)
	v_mfma_f32_16x16x32_bf16 v[66:69], v[94:97], v[70:73], v[66:69]
	global_load_dwordx4 v[70:73], v[112:113], off offset:192
	s_waitcnt vmcnt(5)
	v_mfma_f32_16x16x32_bf16 v[74:77], v[94:97], v[74:77], v[78:81]
	s_nop 2
	global_load_dwordx4 v[78:81], v[114:115], off offset:192
	ds_write_b128 v15, v[2:5]
	ds_write_b128 v15, v[6:9] offset:1024
	ds_write_b128 v15, v[46:49] offset:2048
	ds_write_b128 v15, v[58:61] offset:3072
	ds_write_b128 v15, v[54:57] offset:32768
	s_waitcnt vmcnt(5)
	v_mfma_f32_16x16x32_bf16 v[24:27], v[94:97], v[98:101], v[24:27]
	ds_write_b128 v15, v[62:65] offset:33792
	ds_write_b128 v15, v[20:23] offset:34816
	ds_write_b128 v15, v[50:53] offset:35840
	s_waitcnt vmcnt(3)
	v_mfma_f32_16x16x32_bf16 v[2:5], v[82:85], v[90:93], v[16:19]
	s_waitcnt vmcnt(2)
	v_mfma_f32_16x16x32_bf16 v[6:9], v[82:85], v[86:89], v[66:69]
	s_waitcnt vmcnt(1)
	v_mfma_f32_16x16x32_bf16 v[16:19], v[82:85], v[70:73], v[74:77]
	s_nop 3
	ds_write_b128 v34, v[2:5]
	s_nop 0
	ds_write_b128 v35, v[6:9]
	s_nop 0
	ds_write_b128 v36, v[16:19]
	s_waitcnt vmcnt(0)
	v_mfma_f32_16x16x32_bf16 v[2:5], v[82:85], v[78:81], v[24:27]
	s_nop 7
	ds_write_b128 v37, v[2:5]
	s_waitcnt lgkmcnt(0)
	s_barrier
	s_and_saveexec_b64 s[48:49], s[42:43]
	s_cbranch_execz .LBB0_2283
	v_add_u32_e32 v2, s9, v30
	v_mov_b64_e32 v[4:5], s[4:5]
	s_ashr_i32 s9, s8, 31
	v_mad_i64_i32 v[4:5], s[0:1], v2, s77, v[4:5]
	s_lshl_b64 s[50:51], s[8:9], 1
	v_lshl_add_u64 v[4:5], v[4:5], 0, s[50:51]
	v_mov_b32_e32 v15, v197
	v_lshl_add_u64 v[4:5], v[4:5], 0, v[14:15]
	v_add_co_u32_e32 v6, vcc, 0x6000, v4
	v_add_u32_e32 v50, v31, v33
	ds_read_b128 v[120:123], v50
	ds_read_b128 v[124:127], v50 offset:4096
	ds_read_b128 v[128:131], v50 offset:8192
	ds_read_b128 v[132:135], v50 offset:12288
	ds_read_b128 v[136:139], v50 offset:16384
	ds_read_b128 v[140:143], v50 offset:20480
	ds_read_b128 v[144:147], v50 offset:24576
	ds_read_b128 v[148:151], v50 offset:28672
	s_nop 0
	v_addc_co_u32_e32 v7, vcc, 0, v5, vcc
	global_load_dwordx2 v[22:23], v[6:7], off
	v_add_co_u32_e32 v6, vcc, 0x7000, v4
	v_ashrrev_i32_e32 v3, 31, v2
	s_nop 0
	v_addc_co_u32_e32 v7, vcc, 0, v5, vcc
	v_add_co_u32_e32 v4, vcc, 0x8000, v4
	global_load_dwordx2 v[20:21], v[6:7], off
	s_nop 0
	v_addc_co_u32_e32 v5, vcc, 0, v5, vcc
	global_load_dwordx2 v[4:5], v[4:5], off
	s_nop 0
	v_lshlrev_b64 v[2:3], 12, v[2:3]
	v_lshl_add_u64 v[2:3], s[6:7], 0, v[2:3]
	v_lshl_add_u64 v[2:3], v[2:3], 0, s[50:51]
	v_lshl_add_u64 v[2:3], v[2:3], 0, v[14:15]
	s_waitcnt lgkmcnt(7)
	ds_read_b128 v[152:155], v50 offset:32768
	v_pk_add_f32 v[16:17], v[122:123], 0 op_sel_hi:[1,0]
	v_pk_add_f32 v[18:19], v[120:121], 0 op_sel_hi:[1,0]
	s_nop 0
	s_waitcnt lgkmcnt(7)
	ds_read_b128 v[120:123], v50 offset:36864
	v_pk_add_f32 v[16:17], v[16:17], v[126:127]
	v_pk_add_f32 v[18:19], v[18:19], v[124:125]
	s_nop 0
	s_waitcnt lgkmcnt(7)
	ds_read_b128 v[124:127], v50 offset:40960
	v_pk_add_f32 v[16:17], v[16:17], v[130:131]
	v_pk_add_f32 v[18:19], v[18:19], v[128:129]
	s_nop 0
	s_waitcnt lgkmcnt(7)
	ds_read_b128 v[128:131], v50 offset:45056
	v_pk_add_f32 v[16:17], v[16:17], v[134:135]
	v_pk_add_f32 v[18:19], v[18:19], v[132:133]
	s_nop 0
	s_waitcnt lgkmcnt(7)
	ds_read_b128 v[132:135], v50 offset:49152
	v_pk_add_f32 v[16:17], v[16:17], v[138:139]
	v_pk_add_f32 v[18:19], v[18:19], v[136:137]
	s_nop 0
	s_waitcnt lgkmcnt(7)
	ds_read_b128 v[136:139], v50 offset:53248
	v_pk_add_f32 v[16:17], v[16:17], v[142:143]
	v_pk_add_f32 v[18:19], v[18:19], v[140:141]
	s_nop 0
	s_waitcnt lgkmcnt(7)
	ds_read_b128 v[140:143], v50 offset:57344
	v_pk_add_f32 v[8:9], v[16:17], v[146:147]
	v_pk_add_f32 v[24:25], v[18:19], v[144:145]
	s_nop 0
	s_waitcnt lgkmcnt(7)
	ds_read_b128 v[144:147], v50 offset:61440
	v_pk_add_f32 v[6:7], v[8:9], v[150:151]
	v_pk_add_f32 v[16:17], v[24:25], v[148:149]
	s_waitcnt vmcnt(2)
	v_lshlrev_b32_e32 v8, 16, v22
	v_mul_f32_e32 v8, 0xbfb8aa3b, v8
	v_exp_f32_e32 v8, v8
	v_and_b32_e32 v9, 0xffff0000, v23
	v_mul_f32_e32 v9, 0xbfb8aa3b, v9
	v_exp_f32_e32 v9, v9
	v_add_f32_e32 v8, 1.0, v8
	v_rcp_f32_e32 v18, v8
	v_and_b32_e32 v8, 0xffff0000, v22
	v_mul_f32_e32 v8, 0xbfb8aa3b, v8
	v_exp_f32_e32 v8, v8
	v_add_f32_e32 v9, 1.0, v9
	v_rcp_f32_e32 v9, v9
	v_add_f32_e32 v8, 1.0, v8
	v_rcp_f32_e32 v19, v8
	v_lshlrev_b32_e32 v8, 16, v23
	s_nop 0
	v_mul_f32_e32 v8, 0xbfb8aa3b, v8
	v_exp_f32_e32 v8, v8
	v_pk_fma_f32 v[16:17], v[18:19], v[16:17], 0 op_sel_hi:[1,1,0]
	s_waitcnt lgkmcnt(7)
	ds_read_b128 v[148:151], v38
	v_pk_add_f32 v[26:27], v[154:155], 0 op_sel_hi:[1,0]
	v_pk_add_f32 v[46:47], v[152:153], 0 op_sel_hi:[1,0]
	s_nop 0
	v_add_f32_e32 v8, 1.0, v8
	v_rcp_f32_e32 v8, v8
	s_waitcnt lgkmcnt(7)
	ds_read_b128 v[152:155], v39
	v_pk_add_f32 v[26:27], v[26:27], v[122:123]
	v_pk_add_f32 v[46:47], v[46:47], v[120:121]
	s_nop 0
	v_pk_fma_f32 v[6:7], v[8:9], v[6:7], 0 op_sel_hi:[1,1,0]
	s_waitcnt lgkmcnt(7)
	ds_read_b128 v[120:123], v40
	v_pk_add_f32 v[26:27], v[26:27], v[126:127]
	v_pk_add_f32 v[46:47], v[46:47], v[124:125]
	s_nop 0
	s_waitcnt lgkmcnt(7)
	ds_read_b128 v[124:127], v41
	v_pk_add_f32 v[26:27], v[26:27], v[130:131]
	v_pk_add_f32 v[46:47], v[46:47], v[128:129]
	s_nop 0
	s_waitcnt lgkmcnt(7)
	ds_read_b128 v[128:131], v42
	v_pk_add_f32 v[26:27], v[26:27], v[134:135]
	v_pk_add_f32 v[46:47], v[46:47], v[132:133]
	s_nop 0
	s_waitcnt lgkmcnt(7)
	ds_read_b128 v[132:135], v43
	v_pk_add_f32 v[26:27], v[26:27], v[138:139]
	v_pk_add_f32 v[46:47], v[46:47], v[136:137]
	s_nop 0
	s_waitcnt lgkmcnt(7)
	ds_read_b128 v[136:139], v44
	v_pk_add_f32 v[48:49], v[26:27], v[142:143]
	s_nop 0
	v_pk_add_f32 v[46:47], v[46:47], v[140:141]
	s_waitcnt lgkmcnt(7)
	ds_read_b128 v[140:143], v45
	v_pk_add_f32 v[22:23], v[48:49], v[146:147]
	v_pk_add_f32 v[24:25], v[46:47], v[144:145]
	s_nop 0
	s_waitcnt vmcnt(1)
	v_lshlrev_b32_e32 v26, 16, v20
	v_and_b32_e32 v20, 0xffff0000, v20
	v_mul_f32_e32 v20, 0xbfb8aa3b, v20
	v_exp_f32_e32 v20, v20
	s_waitcnt lgkmcnt(7)
	v_pk_add_f32 v[50:51], v[150:151], 0 op_sel_hi:[1,0]
	v_pk_add_f32 v[52:53], v[148:149], 0 op_sel_hi:[1,0]
	s_nop 0
	v_add_f32_e32 v20, 1.0, v20
	v_rcp_f32_e32 v27, v20
	v_lshlrev_b32_e32 v20, 16, v21
	v_and_b32_e32 v21, 0xffff0000, v21
	s_waitcnt lgkmcnt(6)
	v_pk_add_f32 v[50:51], v[50:51], v[154:155]
	v_pk_add_f32 v[52:53], v[52:53], v[152:153]
	s_nop 0
	v_mul_f32_e32 v26, 0xbfb8aa3b, v26
	v_mul_f32_e32 v20, 0xbfb8aa3b, v20
	v_mul_f32_e32 v21, 0xbfb8aa3b, v21
	v_exp_f32_e32 v26, v26
	s_waitcnt lgkmcnt(5)
	v_pk_add_f32 v[50:51], v[50:51], v[122:123]
	v_pk_add_f32 v[52:53], v[52:53], v[120:121]
	s_nop 0
	v_exp_f32_e32 v20, v20
	v_exp_f32_e32 v21, v21
	v_add_f32_e32 v26, 1.0, v26
	v_rcp_f32_e32 v26, v26
	s_waitcnt lgkmcnt(4)
	v_pk_add_f32 v[50:51], v[50:51], v[126:127]
	v_pk_add_f32 v[52:53], v[52:53], v[124:125]
	s_nop 0
	v_add_f32_e32 v20, 1.0, v20
	v_add_f32_e32 v21, 1.0, v21
	v_rcp_f32_e32 v20, v20
	v_rcp_f32_e32 v21, v21
	s_waitcnt lgkmcnt(3)
	v_pk_add_f32 v[50:51], v[50:51], v[130:131]
	v_pk_add_f32 v[52:53], v[52:53], v[128:129]
	s_nop 0
	v_pk_fma_f32 v[16:17], v[26:27], v[24:25], v[16:17]
	v_pk_fma_f32 v[6:7], v[20:21], v[22:23], v[6:7]
	s_waitcnt lgkmcnt(2)
	v_pk_add_f32 v[50:51], v[50:51], v[134:135]
	v_pk_add_f32 v[52:53], v[52:53], v[132:133]
	s_nop 0
	s_waitcnt lgkmcnt(1)
	v_pk_add_f32 v[50:51], v[50:51], v[138:139]
	v_pk_add_f32 v[52:53], v[52:53], v[136:137]
	s_nop 0
	s_waitcnt lgkmcnt(0)
	v_pk_add_f32 v[48:49], v[50:51], v[142:143]
	s_waitcnt vmcnt(0)
	v_lshlrev_b32_e32 v50, 16, v4
	v_and_b32_e32 v4, 0xffff0000, v4
	v_mul_f32_e32 v4, 0xbfb8aa3b, v4
	v_exp_f32_e32 v4, v4
	v_mul_f32_e32 v50, 0xbfb8aa3b, v50
	v_exp_f32_e32 v50, v50
	v_pk_add_f32 v[46:47], v[52:53], v[140:141]
	v_add_f32_e32 v4, 1.0, v4
	v_rcp_f32_e32 v51, v4
	v_lshlrev_b32_e32 v4, 16, v5
	v_and_b32_e32 v5, 0xffff0000, v5
	v_mul_f32_e32 v4, 0xbfb8aa3b, v4
	v_mul_f32_e32 v5, 0xbfb8aa3b, v5
	v_exp_f32_e32 v4, v4
	v_exp_f32_e32 v5, v5
	v_add_f32_e32 v50, 1.0, v50
	v_rcp_f32_e32 v50, v50
	v_add_f32_e32 v4, 1.0, v4
	v_add_f32_e32 v5, 1.0, v5
	v_rcp_f32_e32 v4, v4
	v_rcp_f32_e32 v5, v5
	v_pk_fma_f32 v[16:17], v[50:51], v[46:47], v[16:17]
	v_pk_fma_f32 v[4:5], v[4:5], v[48:49], v[6:7]
	v_cvt_pk_bf16_f32 v6, v16, v17
	v_cvt_pk_bf16_f32 v7, v4, v5
	global_store_dwordx2 v[2:3], v[6:7], off
	s_branch .LBB0_2283
